# attention window loop: score max tree without self-max canonicalisations (3x max3 + max), loop-invariant bpermute indices hoisted
# baseline (speedup 1.0000x reference)
.LBB0_229:
	s_and_b64 vcc, exec, s[0:1]
	s_cbranch_vccz .LBB0_202
	s_ashr_i32 s2, s24, 1
	s_lshl_b32 s0, s7, 12
	s_lshl_b32 s1, s2, 6
	s_add_i32 s0, s1, s0
	s_lshl_b32 s3, s25, 5
	v_writelane_b32 v255, s34, 29
	s_add_i32 s0, s0, s3
	v_or_b32_e32 v14, s0, v152
	v_writelane_b32 v255, s35, 30
	v_mov_b64_e32 v[10:11], s[70:71]
	v_writelane_b32 v255, s0, 31
	s_waitcnt lgkmcnt(0)
	v_mad_i64_i32 v[0:1], s[0:1], v14, s77, v[10:11]
	v_or_b32_e32 v2, 8, v14
	v_or_b32_e32 v12, 16, v14
	v_or_b32_e32 v14, 24, v14
	s_lshl_b32 s26, s5, 7
	v_mad_i64_i32 v[2:3], s[0:1], v2, s77, v[10:11]
	v_mad_i64_i32 v[12:13], s[0:1], v12, s77, v[10:11]
	v_mad_i64_i32 v[10:11], s[0:1], v14, s77, v[10:11]
	v_lshl_add_u64 v[0:1], v[0:1], 0, s[26:27]
	v_lshl_add_u64 v[2:3], v[2:3], 0, s[26:27]
	v_lshl_add_u64 v[12:13], v[12:13], 0, s[26:27]
	v_lshl_add_u64 v[10:11], v[10:11], 0, s[26:27]
	v_lshl_add_u64 v[0:1], v[0:1], 0, v[8:9]
	v_lshl_add_u64 v[4:5], v[2:3], 0, v[8:9]
	v_lshl_add_u64 v[12:13], v[12:13], 0, v[8:9]
	v_lshl_add_u64 v[14:15], v[10:11], 0, v[8:9]
	global_load_dwordx4 v[0:3], v[0:1], off offset:2048
	s_nop 0
	global_load_dwordx4 v[4:7], v[4:5], off offset:2048
	s_nop 0
	global_load_dwordx4 v[10:13], v[12:13], off offset:2048
	s_nop 0
	global_load_dwordx4 v[14:17], v[14:15], off offset:2048
	s_lshl_b32 s0, s18, 12
	s_lshl_b32 s18, s5, 6
	s_lshl_b32 s7, s7, 3
	s_lshl_b32 s1, s19, 11
	v_writelane_b32 v255, s18, 32
	v_add3_u32 v8, s6, v8, v151
	v_add3_u32 v21, s6, v150, v130
	s_add_i32 s6, s0, 0
	s_max_i32 s18, s2, 4
	s_or_b32 s0, s5, s7
	v_or_b32_e32 v22, s3, v165
	s_add_i32 s3, s6, s1
	s_add_i32 s18, s18, -4
	s_ashr_i32 s1, s0, 31
	v_max_i32_e32 v18, 8, v22
	v_or_b32_e32 v23, 16, v22
	s_min_u32 s26, s18, 56
	s_lshl_b64 s[6:7], s[0:1], 15
	v_add_u32_e32 v18, -8, v18
	v_max_i32_e32 v19, 8, v23
	s_add_u32 s18, s69, s6
	v_mov_b32_e32 v133, v9
	v_min_u32_e32 v24, 48, v18
	v_add_u32_e32 v18, -8, v19
	s_addc_u32 s19, s72, s7
	s_lshl_b32 s5, s26, 13
	s_lshl_b64 s[0:1], s[0:1], 19
	v_min_u32_e32 v25, 48, v18
	v_lshl_add_u64 v[18:19], s[18:19], 0, v[132:133]
	s_add_u32 s18, s75, s0
	s_addc_u32 s19, s76, s1
	s_add_u32 s18, s18, s5
	v_mov_b32_e32 v131, v9
	s_addc_u32 s19, s19, 0
	v_lshl_add_u64 v[140:141], v[18:19], 0, v[130:131]
	v_lshl_add_u64 v[18:19], s[18:19], 0, v[132:133]
	v_readlane_b32 s18, v251, 53
	v_readlane_b32 s19, v251, 54
	s_add_u32 s0, s18, s0
	s_addc_u32 s1, s19, s1
	s_add_u32 s0, s0, s5
	s_addc_u32 s1, s1, 0
	v_lshl_add_u64 v[142:143], v[18:19], 0, v[130:131]
	v_lshl_add_u64 v[18:19], s[0:1], 0, v[132:133]
	s_add_u32 s0, s73, s6
	s_addc_u32 s1, s74, s7
	v_lshl_add_u64 v[144:145], v[18:19], 0, v[130:131]
	v_lshl_add_u64 v[18:19], s[0:1], 0, v[132:133]
	v_lshl_add_u64 v[146:147], v[18:19], 0, v[130:131]
	global_load_dwordx4 v[82:85], v[146:147], off
	global_load_dwordx4 v[74:77], v[146:147], off offset:1024
	v_lshlrev_b32_e32 v20, 3, v166
	s_cmpk_lt_u32 s4, 0x100
	s_movk_i32 s0, 0xffe0
	s_cselect_b64 s[18:19], -1, 0
	s_cmpk_gt_u32 s4, 0xff
	s_cselect_b64 s[24:25], -1, 0
	s_waitcnt vmcnt(5)
	ds_write_b128 v8, v[0:3] offset:34816
	s_waitcnt vmcnt(4)
	ds_write_b128 v8, v[4:7] offset:35968
	s_waitcnt vmcnt(3)
	ds_write_b128 v8, v[10:13] offset:37120
	s_waitcnt vmcnt(2)
	ds_write_b128 v8, v[14:17] offset:38272
	global_load_dwordx4 v[86:89], v[146:147], off offset:2048
	global_load_dwordx4 v[78:81], v[146:147], off offset:3072
	global_load_dwordx4 v[54:57], v[140:141], off
	global_load_dwordx4 v[50:53], v[140:141], off offset:1024
	global_load_dwordx4 v[46:49], v[140:141], off offset:2048
	global_load_dwordx4 v[42:45], v[140:141], off offset:3072
	v_sub_u32_e32 v0, v20, v24
	v_and_b32_e32 v17, -16, v0
	v_cmp_eq_u32_e64 s[4:5], s0, v17
	v_add_u32_e32 v17, 33, v0
	v_cmp_gt_u32_e64 s[44:45], 16, v17
	v_add_u32_e32 v17, 35, v0
	v_cmp_gt_u32_e64 s[48:49], 16, v17
	v_add_u32_e32 v17, 37, v0
	v_sub_u32_e32 v8, v20, v25
	v_add_u32_e32 v18, 34, v0
	v_cmp_gt_u32_e64 s[52:53], 16, v17
	v_add_u32_e32 v17, 39, v0
	v_cmp_gt_u32_e64 s[42:43], 16, v18
	v_add_u32_e32 v18, 36, v0
	v_cmp_gt_u32_e64 s[54:55], 16, v17
	v_and_b32_e32 v17, -16, v8
	v_cmp_gt_u32_e64 s[46:47], 16, v18
	v_add_u32_e32 v18, 38, v0
	v_cmp_eq_u32_e64 s[56:57], s0, v17
	v_add_u32_e32 v17, 33, v8
	v_cmp_gt_u32_e64 s[50:51], 16, v18
	v_add_u32_e32 v18, 34, v8
	v_cmp_gt_u32_e64 s[60:61], 16, v17
	v_add_u32_e32 v17, 35, v8
	v_add_u32_e32 v10, 1, v8
	v_add_u32_e32 v11, 2, v8
	v_writelane_b32 v255, s4, 33
	v_cmp_gt_u32_e64 s[58:59], 16, v18
	v_add_u32_e32 v18, 36, v8
	v_cmp_gt_u32_e64 s[64:65], 16, v17
	v_add_u32_e32 v17, 37, v8
	v_add_u32_e32 v1, 1, v0
	v_add_u32_e32 v2, 2, v0
	v_add_u32_e32 v3, 3, v0
	v_add_u32_e32 v4, 4, v0
	v_add_u32_e32 v5, 5, v0
	v_add_u32_e32 v6, 6, v0
	v_add_u32_e32 v7, 7, v0
	v_add_u32_e32 v12, 3, v8
	v_add_u32_e32 v13, 4, v8
	v_add_u32_e32 v14, 5, v8
	v_add_u32_e32 v15, 6, v8
	v_add_u32_e32 v16, 7, v8
	v_writelane_b32 v255, s5, 34
	v_cmp_gt_u32_e64 s[62:63], 16, v18
	v_add_u32_e32 v18, 38, v8
	v_cmp_gt_u32_e64 s[68:69], 16, v17
	v_add_u32_e32 v17, 39, v8
	v_cmp_gt_u32_e64 s[88:89], 16, v8
	v_cmp_gt_u32_e64 s[4:5], 16, v11
	v_cmp_gt_u32_e64 s[6:7], 16, v10
	v_mov_b32_e32 v8, v9
	v_mov_b32_e32 v10, v9
	v_mov_b32_e32 v11, v9
	v_cmp_gt_u32_e64 s[72:73], 16, v0
	v_cmp_gt_u32_e64 s[74:75], 16, v7
	v_cmp_gt_u32_e64 s[76:77], 16, v6
	v_cmp_gt_u32_e64 s[78:79], 16, v5
	v_cmp_gt_u32_e64 s[80:81], 16, v4
	v_cmp_gt_u32_e64 s[82:83], 16, v3
	v_cmp_gt_u32_e64 s[84:85], 16, v2
	v_cmp_gt_u32_e64 s[86:87], 16, v1
	s_lshl_b32 s26, s26, 5
	s_lshl_b32 s2, s2, 5
	v_mov_b32_e32 v195, v194
	v_mov_b64_e32 v[60:61], v[10:11]
	v_mov_b64_e32 v[64:65], v[10:11]
	v_mov_b64_e32 v[4:5], v[8:9]
	v_mov_b64_e32 v[0:1], v[8:9]
	v_mov_b64_e32 v[104:105], v[10:11]
	v_mov_b64_e32 v[100:101], v[10:11]
	v_mov_b64_e32 v[96:97], v[10:11]
	v_mov_b64_e32 v[92:93], v[10:11]
	v_add_u32_e32 v167, 0x8800, v21
	v_add_u32_e32 v168, 0x9100, v21
	v_cmp_gt_u32_e64 s[66:67], 16, v18
	v_cmp_gt_u32_e64 s[70:71], 16, v17
	v_cmp_gt_u32_e64 s[90:91], 16, v16
	v_cmp_gt_u32_e64 s[92:93], 16, v15
	v_cmp_gt_u32_e64 s[94:95], 16, v14
	v_cmp_gt_u32_e64 s[96:97], 16, v13
	v_cmp_gt_u32_e64 s[0:1], 16, v12
	v_sub_u32_e32 v169, v20, v22
	v_sub_u32_e32 v170, v20, v23
	s_sub_i32 s34, s26, s2
	s_mov_b32 s2, 0
	v_mov_b32_e32 v154, 0
	s_movk_i32 s35, 0x60
	v_mov_b64_e32 v[58:59], v[8:9]
	v_mov_b64_e32 v[62:63], v[8:9]
	v_mov_b64_e32 v[6:7], v[10:11]
	v_mov_b64_e32 v[2:3], v[10:11]
	v_mov_b64_e32 v[102:103], v[8:9]
	v_mov_b64_e32 v[98:99], v[8:9]
	v_mov_b64_e32 v[94:95], v[8:9]
	v_mov_b64_e32 v[90:91], v[8:9]
	v_mov_b64_e32 v[150:151], v[140:141]
	v_mov_b64_e32 v[148:149], v[146:147]
	v_mov_b64_e32 v[152:153], v[194:195]
	v_mov_b32_e32 v8, 0
	v_xor_b32_e32 v184, 16, v220
	v_xor_b32_e32 v185, 32, v220
	v_lshlrev_b32_e32 v184, 2, v184
	v_lshlrev_b32_e32 v185, 2, v185
	s_nop 0
	s_branch .LBB0_235
.LBB0_231:
	s_nop 4
	v_max3_f32 v106, v118, v119, v120
	v_max3_f32 v108, v116, v117, v114
	v_max3_f32 v108, v108, v115, v121
	v_max_f32_e32 v106, v106, v108
	ds_bpermute_b32 v8, v8, v106
	s_waitcnt lgkmcnt(0)
	v_max_f32_e32 v8, v106, v8
	ds_bpermute_b32 v106, v171, v8
	s_waitcnt lgkmcnt(0)
	v_max_f32_e32 v8, v8, v106
	v_cmp_gt_f32_e32 vcc, v8, v153
	s_cbranch_vccz .LBB0_250
	v_max_f32_e32 v8, v8, v8
	v_max_f32_e32 v106, v153, v153
	v_max_f32_e32 v8, v106, v8
	v_sub_f32_e32 v106, v153, v8
	v_exp_f32_e32 v106, v106
	v_mov_b32_e32 v153, v8
	v_mul_f32_e32 v155, v155, v106
	v_pk_mul_f32 v[2:3], v[2:3], v[106:107] op_sel_hi:[1,0]
	v_pk_mul_f32 v[0:1], v[0:1], v[106:107] op_sel_hi:[1,0]
	v_pk_mul_f32 v[6:7], v[6:7], v[106:107] op_sel_hi:[1,0]
	v_pk_mul_f32 v[4:5], v[4:5], v[106:107] op_sel_hi:[1,0]
	v_pk_mul_f32 v[124:125], v[124:125], v[106:107] op_sel_hi:[1,0]
	v_pk_mul_f32 v[122:123], v[122:123], v[106:107] op_sel_hi:[1,0]
	v_pk_mul_f32 v[128:129], v[128:129], v[106:107] op_sel_hi:[1,0]
	v_pk_mul_f32 v[126:127], v[126:127], v[106:107] op_sel_hi:[1,0]

.LBB0_245:
	s_nop 0
	v_max3_f32 v8, v0, v1, v2
	v_max3_f32 v91, v4, v5, v6
	v_max3_f32 v91, v91, v7, v3
	v_max_f32_e32 v90, v8, v91
	v_mov_b32_e32 v8, v184
	ds_bpermute_b32 v92, v8, v90
	s_waitcnt lgkmcnt(0)
	v_max_f32_e32 v90, v90, v92
	v_mov_b32_e32 v171, v185
	ds_bpermute_b32 v91, v171, v90
	s_waitcnt lgkmcnt(0)
	v_max_f32_e32 v90, v90, v91
	v_cmp_gt_f32_e32 vcc, v90, v152
	s_cbranch_vccz .LBB0_251
	v_max_f32_e32 v90, v90, v90
	v_max_f32_e32 v91, v152, v152
	v_max_f32_e32 v122, v91, v90
	v_sub_f32_e32 v90, v152, v122
	v_exp_f32_e32 v102, v90
	v_mov_b32_e32 v123, v153
	v_mov_b32_e32 v155, v139
	v_mov_b64_e32 v[152:153], v[122:123]
	v_mul_f32_e32 v154, v138, v102
	v_pk_mul_f32 v[92:93], v[40:41], v[102:103] op_sel_hi:[1,0]
	v_pk_mul_f32 v[90:91], v[38:39], v[102:103] op_sel_hi:[1,0]
	v_pk_mul_f32 v[96:97], v[36:37], v[102:103] op_sel_hi:[1,0]
	v_pk_mul_f32 v[94:95], v[34:35], v[102:103] op_sel_hi:[1,0]
	v_pk_mul_f32 v[100:101], v[32:33], v[102:103] op_sel_hi:[1,0]
	v_pk_mul_f32 v[98:99], v[30:31], v[102:103] op_sel_hi:[1,0]
	v_pk_mul_f32 v[104:105], v[28:29], v[102:103] op_sel_hi:[1,0]
	v_pk_mul_f32 v[102:103], v[26:27], v[102:103] op_sel_hi:[1,0]
	s_branch .LBB0_252

.LBB0_257:
	s_nop 3
	v_max3_f32 v74, v0, v1, v2
	v_max3_f32 v76, v4, v5, v6
	v_max3_f32 v76, v76, v7, v3
	v_max_f32_e32 v74, v74, v76
	ds_bpermute_b32 v75, v8, v74
	s_waitcnt lgkmcnt(0)
	v_max_f32_e32 v74, v74, v75
	ds_bpermute_b32 v75, v171, v74
	s_waitcnt lgkmcnt(0)
	v_max_f32_e32 v74, v74, v75
	v_cmp_gt_f32_e32 vcc, v74, v153
	s_cbranch_vccz .LBB0_260
	v_max_f32_e32 v74, v74, v74
	v_max_f32_e32 v75, v153, v153
	v_max_f32_e32 v122, v75, v74
	v_sub_f32_e32 v74, v153, v122
	v_exp_f32_e32 v74, v74
	v_mov_b32_e32 v153, v122
	v_mul_f32_e32 v155, v155, v74
	v_pk_mul_f32 v[88:89], v[24:25], v[74:75] op_sel_hi:[1,0]
	v_pk_mul_f32 v[86:87], v[22:23], v[74:75] op_sel_hi:[1,0]
	v_pk_mul_f32 v[84:85], v[20:21], v[74:75] op_sel_hi:[1,0]
	v_pk_mul_f32 v[82:83], v[18:19], v[74:75] op_sel_hi:[1,0]
	v_pk_mul_f32 v[80:81], v[16:17], v[74:75] op_sel_hi:[1,0]
	v_pk_mul_f32 v[78:79], v[14:15], v[74:75] op_sel_hi:[1,0]
	v_pk_mul_f32 v[76:77], v[12:13], v[74:75] op_sel_hi:[1,0]
	v_pk_mul_f32 v[74:75], v[10:11], v[74:75] op_sel_hi:[1,0]
	s_branch .LBB0_261

.LBB0_269:
	s_nop 2
	v_max3_f32 v130, v160, v161, v162
	v_max3_f32 v132, v158, v159, v156
	v_max3_f32 v132, v132, v157, v163
	v_max_f32_e32 v130, v130, v132
	ds_bpermute_b32 v131, v8, v130
	s_waitcnt lgkmcnt(0)
	v_max_f32_e32 v130, v130, v131
	ds_bpermute_b32 v131, v171, v130
	s_waitcnt lgkmcnt(0)
	v_max_f32_e32 v130, v130, v131
	v_cmp_gt_f32_e32 vcc, v130, v152
	s_cbranch_vccz .LBB0_271
	v_max_f32_e32 v130, v130, v130
	v_max_f32_e32 v131, v152, v152
	v_max_f32_e32 v130, v131, v130
	v_sub_f32_e32 v131, v152, v130
	v_exp_f32_e32 v132, v131
	v_mov_b32_e32 v131, v153
	v_mov_b64_e32 v[152:153], v[130:131]
	v_mul_f32_e32 v154, v154, v132
	v_pk_mul_f32 v[92:93], v[92:93], v[132:133] op_sel_hi:[1,0]
	v_pk_mul_f32 v[90:91], v[90:91], v[132:133] op_sel_hi:[1,0]
	v_pk_mul_f32 v[96:97], v[96:97], v[132:133] op_sel_hi:[1,0]
	v_pk_mul_f32 v[94:95], v[94:95], v[132:133] op_sel_hi:[1,0]
	v_pk_mul_f32 v[100:101], v[100:101], v[132:133] op_sel_hi:[1,0]
	v_pk_mul_f32 v[98:99], v[98:99], v[132:133] op_sel_hi:[1,0]
	v_pk_mul_f32 v[104:105], v[104:105], v[132:133] op_sel_hi:[1,0]
	v_pk_mul_f32 v[102:103], v[102:103], v[132:133] op_sel_hi:[1,0]
	s_branch .LBB0_272
